# grid barrier: L1 invalidate issued at arrival (overlaps the atomics/polling) instead of after the release
# speedup vs baseline: 1.0147x; 1.0076x over previous
.LBB0_116:
	v_mov_b32_e32 v0, 0x23fb0
	v_mov_b32_e32 v1, 0x23fb4
	ds_read_b32 v0, v0
	ds_read_b32 v1, v1
	s_getreg_b32 s0, hwreg(HW_REG_XCC_ID, 0, 4)
	s_waitcnt vmcnt(0)
	s_waitcnt lgkmcnt(0)
	v_readfirstlane_b32 s34, v0
	v_readfirstlane_b32 s35, v1
	s_barrier
	s_mov_b64 s[30:31], exec
	v_readlane_b32 s2, v255, 0
	v_readlane_b32 s3, v255, 1
	s_and_b64 s[2:3], s[30:31], s[2:3]
	s_mov_b64 exec, s[2:3]
	s_cbranch_execz .LBB0_160
	v_mov_b32_e32 v0, 0x23e00
	s_waitcnt vmcnt(0) expcnt(0) lgkmcnt(0)
	buffer_inv sc1
	ds_read_b32 v2, v0
	v_mov_b32_e32 v0, 0x23e04
	ds_read_b32 v0, v0
	s_and_b32 s36, s0, 15
	s_waitcnt lgkmcnt(1)
	v_cmp_ne_u32_e32 vcc, 0, v2
	s_cbranch_vccnz .LBB0_131
	v_readlane_b32 s0, v255, 2
	v_readlane_b32 s1, v255, 3
	s_mul_i32 s20, s1, s33
	s_mul_i32 s20, s20, s0
	s_add_u32 s0, s34, 0x600200
	s_addc_u32 s1, s35, 0
	s_add_u32 s4, s34, 0x600400
	s_addc_u32 s5, s35, 0
	s_add_u32 s6, s34, 0x600500
	s_addc_u32 s7, s35, 0
	s_add_u32 s8, s34, 0x600600
	s_addc_u32 s9, s35, 0
	s_add_u32 s10, s34, 0x600700
	s_addc_u32 s11, s35, 0
	s_add_u32 s12, s34, 0x600800
	s_addc_u32 s13, s35, 0
	s_add_u32 s14, s34, 0x600900
	s_addc_u32 s15, s35, 0
	s_add_u32 s16, s34, 0x600a00
	s_addc_u32 s17, s35, 0
	s_add_u32 s18, s34, 0x600b00
	s_addc_u32 s19, s35, 0
	s_add_u32 s22, s34, 0x600c00
	s_addc_u32 s23, s35, 0
	s_add_u32 s24, s34, 0x600d00
	s_addc_u32 s25, s35, 0
	s_add_u32 s26, s34, 0x600e00
	s_addc_u32 s27, s35, 0
	s_add_u32 s28, s34, 0x600f00
	s_addc_u32 s29, s35, 0
	s_add_u32 s38, s34, 0x601000
	s_addc_u32 s39, s35, 0
	s_add_u32 s40, s34, 0x601100
	s_addc_u32 s41, s35, 0
	s_add_u32 s42, s34, 0x601200
	s_addc_u32 s43, s35, 0
	s_add_u32 s44, s34, 0x601300
	s_addc_u32 s45, s35, 0
	s_mov_b32 s21, 1
	s_mov_b64 s[2:3], 0
	s_waitcnt lgkmcnt(0)
	v_mov_b64_e32 v[0:1], s[4:5]
	v_mov_b64_e32 v[2:3], s[6:7]
	v_mov_b64_e32 v[4:5], s[8:9]
	v_mov_b64_e32 v[6:7], s[10:11]
	v_mov_b64_e32 v[8:9], s[12:13]
	v_mov_b64_e32 v[10:11], s[14:15]
	v_mov_b64_e32 v[12:13], s[16:17]
	v_mov_b64_e32 v[14:15], s[18:19]
	v_mov_b64_e32 v[16:17], s[22:23]
	v_mov_b64_e32 v[18:19], s[24:25]
	v_mov_b64_e32 v[20:21], s[26:27]
	v_mov_b64_e32 v[22:23], s[28:29]
	v_mov_b64_e32 v[24:25], s[38:39]
	v_mov_b64_e32 v[26:27], s[40:41]
	v_mov_b64_e32 v[28:29], s[42:43]
	v_mov_b64_e32 v[30:31], s[44:45]
	s_branch .LBB0_121

.LBB0_143:
	s_or_b64 exec, exec, s[2:3]
	s_waitcnt vmcnt(0) lgkmcnt(0)
	s_waitcnt vmcnt(0)

.LBB0_159:
	s_or_b64 exec, exec, s[0:1]
	v_mov_b32_e32 v0, s23
	v_add_co_u32_e32 v0, vcc, 0x2000, v0
	v_mov_b32_e32 v1, s22
	s_nop 0
	v_addc_co_u32_e32 v1, vcc, 0, v1, vcc
	v_mov_b32_e32 v2, 1
	s_waitcnt vmcnt(0) lgkmcnt(0)
	flat_atomic_add v[0:1], v2 offset:1024
	s_waitcnt vmcnt(0)

.LBB0_195:
	ds_read_b32 v0, v82
	ds_read_b32 v1, v83
	s_getreg_b32 s0, hwreg(HW_REG_XCC_ID, 0, 4)
	s_waitcnt vmcnt(0)
	s_waitcnt lgkmcnt(0)
	v_readfirstlane_b32 s34, v0
	v_readfirstlane_b32 s35, v1
	s_barrier
	s_mov_b64 s[30:31], exec
	v_readlane_b32 s2, v255, 0
	v_readlane_b32 s3, v255, 1
	s_and_b64 s[2:3], s[30:31], s[2:3]
	s_mov_b64 exec, s[2:3]
	s_cbranch_execz .LBB0_239
	v_mov_b32_e32 v0, 0x23e00
	s_waitcnt vmcnt(0) expcnt(0) lgkmcnt(0)
	buffer_inv sc1
	ds_read_b32 v2, v0
	v_mov_b32_e32 v0, 0x23e04
	ds_read_b32 v0, v0
	s_and_b32 s36, s0, 15
	s_waitcnt lgkmcnt(1)
	v_cmp_ne_u32_e32 vcc, 0, v2
	s_cbranch_vccnz .LBB0_210
	v_readlane_b32 s0, v255, 2
	v_readlane_b32 s1, v255, 3
	s_mul_i32 s20, s1, s33
	s_mul_i32 s20, s20, s0
	s_add_u32 s0, s34, 0x600200
	s_addc_u32 s1, s35, 0
	s_add_u32 s4, s34, 0x600400
	s_addc_u32 s5, s35, 0
	s_add_u32 s6, s34, 0x600500
	s_addc_u32 s7, s35, 0
	s_add_u32 s8, s34, 0x600600
	s_addc_u32 s9, s35, 0
	s_add_u32 s10, s34, 0x600700
	s_addc_u32 s11, s35, 0
	s_add_u32 s12, s34, 0x600800
	s_addc_u32 s13, s35, 0
	s_add_u32 s14, s34, 0x600900
	s_addc_u32 s15, s35, 0
	s_add_u32 s16, s34, 0x600a00
	s_addc_u32 s17, s35, 0
	s_add_u32 s18, s34, 0x600b00
	s_addc_u32 s19, s35, 0
	s_add_u32 s22, s34, 0x600c00
	s_addc_u32 s23, s35, 0
	s_add_u32 s24, s34, 0x600d00
	s_addc_u32 s25, s35, 0
	s_add_u32 s26, s34, 0x600e00
	s_addc_u32 s27, s35, 0
	s_add_u32 s28, s34, 0x600f00
	s_addc_u32 s29, s35, 0
	s_add_u32 s38, s34, 0x601000
	s_addc_u32 s39, s35, 0
	s_add_u32 s40, s34, 0x601100
	s_addc_u32 s41, s35, 0
	s_add_u32 s42, s34, 0x601200
	s_addc_u32 s43, s35, 0
	s_add_u32 s44, s34, 0x601300
	s_addc_u32 s45, s35, 0
	s_mov_b32 s21, 1
	s_mov_b64 s[2:3], 0
	s_waitcnt lgkmcnt(0)
	v_mov_b64_e32 v[0:1], s[4:5]
	v_mov_b64_e32 v[2:3], s[6:7]
	v_mov_b64_e32 v[4:5], s[8:9]
	v_mov_b64_e32 v[6:7], s[10:11]
	v_mov_b64_e32 v[8:9], s[12:13]
	v_mov_b64_e32 v[10:11], s[14:15]
	v_mov_b64_e32 v[12:13], s[16:17]
	v_mov_b64_e32 v[14:15], s[18:19]
	v_mov_b64_e32 v[16:17], s[22:23]
	v_mov_b64_e32 v[18:19], s[24:25]
	v_mov_b64_e32 v[20:21], s[26:27]
	v_mov_b64_e32 v[22:23], s[28:29]
	v_mov_b64_e32 v[24:25], s[38:39]
	v_mov_b64_e32 v[26:27], s[40:41]
	v_mov_b64_e32 v[28:29], s[42:43]
	v_mov_b64_e32 v[30:31], s[44:45]
	s_branch .LBB0_200

.LBB0_240:
	s_or_b64 exec, exec, s[0:1]
	v_mov_b32_e32 v0, s23
	v_add_co_u32_e32 v0, vcc, 0x2000, v0
	v_mov_b32_e32 v1, s22
	s_nop 0
	v_addc_co_u32_e32 v1, vcc, 0, v1, vcc
	s_waitcnt vmcnt(0) lgkmcnt(0)
	flat_atomic_add v[0:1], v219 offset:1024
	s_waitcnt vmcnt(0)

.LBB0_261:
	ds_read_b32 v0, v214
	s_waitcnt lgkmcnt(0)
	v_readfirstlane_b32 s44, v0
	ds_read_b32 v0, v215
	s_getreg_b32 s0, hwreg(HW_REG_XCC_ID, 0, 4)
	s_waitcnt vmcnt(0)
	s_waitcnt lgkmcnt(0)
	s_barrier
	v_readfirstlane_b32 s62, v0
	s_mov_b64 s[38:39], exec
	v_readlane_b32 s2, v255, 0
	v_readlane_b32 s3, v255, 1
	s_and_b64 s[2:3], s[38:39], s[2:3]
	s_mov_b64 exec, s[2:3]
	s_cbranch_execz .LBB0_305
	s_waitcnt vmcnt(0) expcnt(0) lgkmcnt(0)
	buffer_inv sc1
	ds_read_b32 v2, v217
	ds_read_b32 v0, v218
	s_and_b32 s63, s0, 15
	s_waitcnt lgkmcnt(1)
	v_cmp_ne_u32_e32 vcc, 0, v2
	s_cbranch_vccnz .LBB0_276
	s_add_u32 s0, s44, 0x600200
	s_addc_u32 s1, s62, 0
	s_add_u32 s2, s44, 0x600400
	s_addc_u32 s3, s62, 0
	s_add_u32 s4, s44, 0x600500
	s_addc_u32 s5, s62, 0
	s_add_u32 s6, s44, 0x600600
	s_addc_u32 s7, s62, 0
	s_add_u32 s8, s44, 0x600700
	s_addc_u32 s9, s62, 0
	s_add_u32 s10, s44, 0x600800
	s_addc_u32 s11, s62, 0
	s_add_u32 s12, s44, 0x600900
	s_addc_u32 s13, s62, 0
	s_add_u32 s14, s44, 0x600a00
	s_addc_u32 s15, s62, 0
	s_add_u32 s16, s44, 0x600b00
	s_addc_u32 s17, s62, 0
	s_add_u32 s18, s44, 0x600c00
	s_addc_u32 s19, s62, 0
	s_add_u32 s20, s44, 0x600d00
	s_addc_u32 s21, s62, 0
	s_add_u32 s22, s44, 0x600e00
	s_addc_u32 s23, s62, 0
	s_add_u32 s24, s44, 0x600f00
	s_addc_u32 s25, s62, 0
	s_add_u32 s26, s44, 0x601000
	s_addc_u32 s27, s62, 0
	s_add_u32 s28, s44, 0x601100
	s_addc_u32 s29, s62, 0
	s_add_u32 s40, s44, 0x601200
	s_addc_u32 s41, s62, 0
	s_add_u32 s42, s44, 0x601300
	s_addc_u32 s43, s62, 0
	s_mov_b32 s64, 1
	s_mov_b64 s[48:49], 0
	s_branch .LBB0_266

.LBB0_360:
	ds_read_b32 v0, v214
	s_waitcnt lgkmcnt(0)
	v_readfirstlane_b32 s43, v0
	ds_read_b32 v0, v215
	s_getreg_b32 s0, hwreg(HW_REG_XCC_ID, 0, 4)
	s_waitcnt vmcnt(0)
	s_waitcnt lgkmcnt(0)
	s_barrier
	v_readfirstlane_b32 s44, v0
	s_mov_b64 s[38:39], exec
	v_readlane_b32 s2, v255, 0
	v_readlane_b32 s3, v255, 1
	s_and_b64 s[2:3], s[38:39], s[2:3]
	s_mov_b64 exec, s[2:3]
	s_cbranch_execz .LBB0_404
	s_waitcnt vmcnt(0) expcnt(0) lgkmcnt(0)
	buffer_inv sc1
	ds_read_b32 v2, v217
	ds_read_b32 v0, v218
	s_and_b32 s62, s0, 15
	s_waitcnt lgkmcnt(1)
	v_cmp_ne_u32_e32 vcc, 0, v2
	s_cbranch_vccnz .LBB0_375
	s_add_u32 s0, s43, 0x600200
	s_addc_u32 s1, s44, 0
	s_add_u32 s2, s43, 0x600400
	s_addc_u32 s3, s44, 0
	s_add_u32 s4, s43, 0x600500
	s_addc_u32 s5, s44, 0
	s_add_u32 s6, s43, 0x600600
	s_addc_u32 s7, s44, 0
	s_add_u32 s8, s43, 0x600700
	s_addc_u32 s9, s44, 0
	s_add_u32 s10, s43, 0x600800
	s_addc_u32 s11, s44, 0
	s_add_u32 s12, s43, 0x600900
	s_addc_u32 s13, s44, 0
	s_add_u32 s14, s43, 0x600a00
	s_addc_u32 s15, s44, 0
	s_add_u32 s16, s43, 0x600b00
	s_addc_u32 s17, s44, 0
	s_add_u32 s18, s43, 0x600c00
	s_addc_u32 s19, s44, 0
	s_add_u32 s20, s43, 0x600d00
	s_addc_u32 s21, s44, 0
	s_add_u32 s22, s43, 0x600e00
	s_addc_u32 s23, s44, 0
	s_add_u32 s24, s43, 0x600f00
	s_addc_u32 s25, s44, 0
	s_add_u32 s26, s43, 0x601000
	s_addc_u32 s27, s44, 0
	s_add_u32 s28, s43, 0x601100
	s_addc_u32 s29, s44, 0
	s_add_u32 s50, s43, 0x601200
	s_addc_u32 s51, s44, 0
	s_add_u32 s52, s43, 0x601300
	s_addc_u32 s53, s44, 0
	s_mov_b32 s63, 1
	s_mov_b64 s[54:55], 0
	s_branch .LBB0_365

.LBB0_432:
	ds_read_b32 v0, v214
	s_waitcnt lgkmcnt(0)
	v_readfirstlane_b32 s43, v0
	ds_read_b32 v0, v215
	s_getreg_b32 s0, hwreg(HW_REG_XCC_ID, 0, 4)
	s_waitcnt vmcnt(0)
	s_waitcnt lgkmcnt(0)
	s_barrier
	v_readfirstlane_b32 s44, v0
	s_mov_b64 s[40:41], exec
	v_readlane_b32 s2, v255, 0
	v_readlane_b32 s3, v255, 1
	s_and_b64 s[2:3], s[40:41], s[2:3]
	s_mov_b64 exec, s[2:3]
	s_cbranch_execz .LBB0_476
	s_waitcnt vmcnt(0) expcnt(0) lgkmcnt(0)
	buffer_inv sc1
	ds_read_b32 v2, v217
	ds_read_b32 v0, v218
	s_and_b32 s62, s0, 15
	s_waitcnt lgkmcnt(1)
	v_cmp_ne_u32_e32 vcc, 0, v2
	s_cbranch_vccnz .LBB0_447
	s_add_u32 s0, s43, 0x600200
	s_addc_u32 s1, s44, 0
	s_add_u32 s2, s43, 0x600400
	s_addc_u32 s3, s44, 0
	s_add_u32 s4, s43, 0x600500
	s_addc_u32 s5, s44, 0
	s_add_u32 s6, s43, 0x600600
	s_addc_u32 s7, s44, 0
	s_add_u32 s8, s43, 0x600700
	s_addc_u32 s9, s44, 0
	s_add_u32 s10, s43, 0x600800
	s_addc_u32 s11, s44, 0
	s_add_u32 s12, s43, 0x600900
	s_addc_u32 s13, s44, 0
	s_add_u32 s14, s43, 0x600a00
	s_addc_u32 s15, s44, 0
	s_add_u32 s16, s43, 0x600b00
	s_addc_u32 s17, s44, 0
	s_add_u32 s18, s43, 0x600c00
	s_addc_u32 s19, s44, 0
	s_add_u32 s20, s43, 0x600d00
	s_addc_u32 s21, s44, 0
	s_add_u32 s22, s43, 0x600e00
	s_addc_u32 s23, s44, 0
	s_add_u32 s24, s43, 0x600f00
	s_addc_u32 s25, s44, 0
	s_add_u32 s26, s43, 0x601000
	s_addc_u32 s27, s44, 0
	s_add_u32 s28, s43, 0x601100
	s_addc_u32 s29, s44, 0
	s_add_u32 s50, s43, 0x601200
	s_addc_u32 s51, s44, 0
	s_add_u32 s52, s43, 0x601300
	s_addc_u32 s53, s44, 0
	s_mov_b32 s63, 1
	s_mov_b64 s[54:55], 0
	s_branch .LBB0_437

.LBB0_509:
	ds_read_b32 v0, v214
	s_waitcnt lgkmcnt(0)
	v_readfirstlane_b32 s43, v0
	ds_read_b32 v0, v215
	s_getreg_b32 s0, hwreg(HW_REG_XCC_ID, 0, 4)
	s_waitcnt vmcnt(0)
	s_waitcnt lgkmcnt(0)
	s_barrier
	v_readfirstlane_b32 s44, v0
	s_mov_b64 s[48:49], exec
	v_readlane_b32 s2, v255, 0
	v_readlane_b32 s3, v255, 1
	s_and_b64 s[2:3], s[48:49], s[2:3]
	s_mov_b64 exec, s[2:3]
	s_cbranch_execz .LBB0_553
	s_waitcnt vmcnt(0) expcnt(0) lgkmcnt(0)
	buffer_inv sc1
	ds_read_b32 v2, v217
	ds_read_b32 v0, v218
	s_and_b32 s62, s0, 15
	s_waitcnt lgkmcnt(1)
	v_cmp_ne_u32_e32 vcc, 0, v2
	s_cbranch_vccnz .LBB0_524
	s_add_u32 s0, s43, 0x600200
	s_addc_u32 s1, s44, 0
	s_add_u32 s2, s43, 0x600400
	s_addc_u32 s3, s44, 0
	s_add_u32 s4, s43, 0x600500
	s_addc_u32 s5, s44, 0
	s_add_u32 s6, s43, 0x600600
	s_addc_u32 s7, s44, 0
	s_add_u32 s8, s43, 0x600700
	s_addc_u32 s9, s44, 0
	s_add_u32 s10, s43, 0x600800
	s_addc_u32 s11, s44, 0
	s_add_u32 s12, s43, 0x600900
	s_addc_u32 s13, s44, 0
	s_add_u32 s14, s43, 0x600a00
	s_addc_u32 s15, s44, 0
	s_add_u32 s16, s43, 0x600b00
	s_addc_u32 s17, s44, 0
	s_add_u32 s18, s43, 0x600c00
	s_addc_u32 s19, s44, 0
	s_add_u32 s20, s43, 0x600d00
	s_addc_u32 s21, s44, 0
	s_add_u32 s22, s43, 0x600e00
	s_addc_u32 s23, s44, 0
	s_add_u32 s24, s43, 0x600f00
	s_addc_u32 s25, s44, 0
	s_add_u32 s26, s43, 0x601000
	s_addc_u32 s27, s44, 0
	s_add_u32 s28, s43, 0x601100
	s_addc_u32 s29, s44, 0
	s_add_u32 s52, s43, 0x601200
	s_addc_u32 s53, s44, 0
	s_add_u32 s54, s43, 0x601300
	s_addc_u32 s55, s44, 0
	s_mov_b32 s63, 1
	s_mov_b64 s[56:57], 0
	s_branch .LBB0_514

.LBB0_579:
	ds_read_b32 v0, v214
	s_waitcnt lgkmcnt(0)
	v_readfirstlane_b32 s43, v0
	ds_read_b32 v0, v215
	s_getreg_b32 s0, hwreg(HW_REG_XCC_ID, 0, 4)
	s_waitcnt vmcnt(0)
	s_waitcnt lgkmcnt(0)
	s_barrier
	v_readfirstlane_b32 s44, v0
	s_mov_b64 s[38:39], exec
	v_readlane_b32 s2, v255, 0
	v_readlane_b32 s3, v255, 1
	s_and_b64 s[2:3], s[38:39], s[2:3]
	s_mov_b64 exec, s[2:3]
	s_cbranch_execz .LBB0_623
	s_waitcnt vmcnt(0) expcnt(0) lgkmcnt(0)
	buffer_inv sc1
	ds_read_b32 v2, v217
	ds_read_b32 v0, v218
	s_and_b32 s62, s0, 15
	s_waitcnt lgkmcnt(1)
	v_cmp_ne_u32_e32 vcc, 0, v2
	s_cbranch_vccnz .LBB0_594
	s_add_u32 s0, s43, 0x600200
	s_addc_u32 s1, s44, 0
	s_add_u32 s2, s43, 0x600400
	s_addc_u32 s3, s44, 0
	s_add_u32 s4, s43, 0x600500
	s_addc_u32 s5, s44, 0
	s_add_u32 s6, s43, 0x600600
	s_addc_u32 s7, s44, 0
	s_add_u32 s8, s43, 0x600700
	s_addc_u32 s9, s44, 0
	s_add_u32 s10, s43, 0x600800
	s_addc_u32 s11, s44, 0
	s_add_u32 s12, s43, 0x600900
	s_addc_u32 s13, s44, 0
	s_add_u32 s14, s43, 0x600a00
	s_addc_u32 s15, s44, 0
	s_add_u32 s16, s43, 0x600b00
	s_addc_u32 s17, s44, 0
	s_add_u32 s18, s43, 0x600c00
	s_addc_u32 s19, s44, 0
	s_add_u32 s20, s43, 0x600d00
	s_addc_u32 s21, s44, 0
	s_add_u32 s22, s43, 0x600e00
	s_addc_u32 s23, s44, 0
	s_add_u32 s24, s43, 0x600f00
	s_addc_u32 s25, s44, 0
	s_add_u32 s26, s43, 0x601000
	s_addc_u32 s27, s44, 0
	s_add_u32 s28, s43, 0x601100
	s_addc_u32 s29, s44, 0
	s_add_u32 s40, s43, 0x601200
	s_addc_u32 s41, s44, 0
	s_add_u32 s46, s43, 0x601300
	s_addc_u32 s47, s44, 0
	s_mov_b32 s63, 1
	s_mov_b64 s[48:49], 0
	s_branch .LBB0_584

.LBB0_647:
	ds_read_b32 v0, v214
	s_waitcnt lgkmcnt(0)
	v_readfirstlane_b32 s37, v0
	ds_read_b32 v0, v215
	s_getreg_b32 s0, hwreg(HW_REG_XCC_ID, 0, 4)
	s_waitcnt vmcnt(0)
	s_waitcnt vmcnt(0) lgkmcnt(0)
	s_barrier
	v_readfirstlane_b32 s42, v0
	s_mov_b64 s[46:47], exec
	v_readlane_b32 s2, v255, 0
	v_readlane_b32 s3, v255, 1
	s_and_b64 s[2:3], s[46:47], s[2:3]
	s_mov_b64 exec, s[2:3]
	s_cbranch_execz .LBB0_691
	s_waitcnt vmcnt(0) expcnt(0) lgkmcnt(0)
	buffer_inv sc1
	ds_read_b32 v2, v217
	ds_read_b32 v0, v218
	s_and_b32 s43, s0, 15
	s_waitcnt lgkmcnt(1)
	v_cmp_ne_u32_e32 vcc, 0, v2
	s_cbranch_vccnz .LBB0_662
	s_add_u32 s0, s37, 0x600200
	s_addc_u32 s1, s42, 0
	s_add_u32 s2, s37, 0x600400
	s_addc_u32 s3, s42, 0
	s_add_u32 s4, s37, 0x600500
	s_addc_u32 s5, s42, 0
	s_add_u32 s6, s37, 0x600600
	s_addc_u32 s7, s42, 0
	s_add_u32 s8, s37, 0x600700
	s_addc_u32 s9, s42, 0
	s_add_u32 s10, s37, 0x600800
	s_addc_u32 s11, s42, 0
	s_add_u32 s12, s37, 0x600900
	s_addc_u32 s13, s42, 0
	s_add_u32 s14, s37, 0x600a00
	s_addc_u32 s15, s42, 0
	s_add_u32 s16, s37, 0x600b00
	s_addc_u32 s17, s42, 0
	s_add_u32 s18, s37, 0x600c00
	s_addc_u32 s19, s42, 0
	s_add_u32 s20, s37, 0x600d00
	s_addc_u32 s21, s42, 0
	s_add_u32 s22, s37, 0x600e00
	s_addc_u32 s23, s42, 0
	s_add_u32 s24, s37, 0x600f00
	s_addc_u32 s25, s42, 0
	s_add_u32 s26, s37, 0x601000
	s_addc_u32 s27, s42, 0
	s_add_u32 s28, s37, 0x601100
	s_addc_u32 s29, s42, 0
	s_add_u32 s48, s37, 0x601200
	s_addc_u32 s49, s42, 0
	s_add_u32 s50, s37, 0x601300
	s_addc_u32 s51, s42, 0
	s_mov_b32 s44, 1
	s_mov_b64 s[52:53], 0
	s_branch .LBB0_652

.LBB0_700:
	s_or_b64 exec, exec, s[16:17]
	ds_read_b32 v0, v214
	s_waitcnt lgkmcnt(0)
	v_readfirstlane_b32 s37, v0
	ds_read_b32 v0, v215
	s_getreg_b32 s0, hwreg(HW_REG_XCC_ID, 0, 4)
	s_waitcnt vmcnt(0)
	s_waitcnt lgkmcnt(0)
	s_barrier
	v_readfirstlane_b32 s42, v0
	s_mov_b64 s[38:39], exec
	v_readlane_b32 s2, v255, 0
	v_readlane_b32 s3, v255, 1
	s_and_b64 s[2:3], s[38:39], s[2:3]
	s_mov_b64 exec, s[2:3]
	s_cbranch_execz .LBB0_744
	s_waitcnt vmcnt(0) expcnt(0) lgkmcnt(0)
	buffer_inv sc1
	ds_read_b32 v2, v217
	ds_read_b32 v0, v218
	s_and_b32 s43, s0, 15
	s_waitcnt lgkmcnt(1)
	v_cmp_ne_u32_e32 vcc, 0, v2
	s_cbranch_vccnz .LBB0_715
	s_add_u32 s0, s37, 0x600200
	s_addc_u32 s1, s42, 0
	s_add_u32 s2, s37, 0x600400
	s_addc_u32 s3, s42, 0
	s_add_u32 s4, s37, 0x600500
	s_addc_u32 s5, s42, 0
	s_add_u32 s6, s37, 0x600600
	s_addc_u32 s7, s42, 0
	s_add_u32 s8, s37, 0x600700
	s_addc_u32 s9, s42, 0
	s_add_u32 s10, s37, 0x600800
	s_addc_u32 s11, s42, 0
	s_add_u32 s12, s37, 0x600900
	s_addc_u32 s13, s42, 0
	s_add_u32 s14, s37, 0x600a00
	s_addc_u32 s15, s42, 0
	s_add_u32 s16, s37, 0x600b00
	s_addc_u32 s17, s42, 0
	s_add_u32 s18, s37, 0x600c00
	s_addc_u32 s19, s42, 0
	s_add_u32 s20, s37, 0x600d00
	s_addc_u32 s21, s42, 0
	s_add_u32 s22, s37, 0x600e00
	s_addc_u32 s23, s42, 0
	s_add_u32 s24, s37, 0x600f00
	s_addc_u32 s25, s42, 0
	s_add_u32 s26, s37, 0x601000
	s_addc_u32 s27, s42, 0
	s_add_u32 s28, s37, 0x601100
	s_addc_u32 s29, s42, 0
	s_add_u32 s40, s37, 0x601200
	s_addc_u32 s41, s42, 0
	s_add_u32 s46, s37, 0x601300
	s_addc_u32 s47, s42, 0
	s_mov_b32 s44, 1
	s_mov_b64 s[48:49], 0
	s_branch .LBB0_705

.LBB0_1289:
	s_andn2_b64 vcc, exec, s[12:13]
	s_cbranch_vccnz .LBB0_1341
	ds_read_b32 v0, v214
	s_waitcnt lgkmcnt(0)
	v_readfirstlane_b32 s37, v0
	ds_read_b32 v0, v215
	s_getreg_b32 s0, hwreg(HW_REG_XCC_ID, 0, 4)
	s_waitcnt vmcnt(0)
	s_waitcnt vmcnt(0) lgkmcnt(0)
	s_barrier
	v_readfirstlane_b32 s44, v0
	s_mov_b64 s[38:39], exec
	v_readlane_b32 s2, v255, 0
	v_readlane_b32 s3, v255, 1
	s_and_b64 s[2:3], s[38:39], s[2:3]
	s_mov_b64 exec, s[2:3]
	s_cbranch_execz .LBB0_1334
	s_waitcnt vmcnt(0) expcnt(0) lgkmcnt(0)
	buffer_inv sc1
	ds_read_b32 v2, v217
	ds_read_b32 v0, v218
	s_and_b32 s62, s0, 15
	s_waitcnt lgkmcnt(1)
	v_cmp_ne_u32_e32 vcc, 0, v2
	s_cbranch_vccnz .LBB0_1305
	s_add_u32 s0, s37, 0x600200
	s_addc_u32 s1, s44, 0
	s_add_u32 s2, s37, 0x600400
	s_addc_u32 s3, s44, 0
	s_add_u32 s4, s37, 0x600500
	s_addc_u32 s5, s44, 0
	s_add_u32 s6, s37, 0x600600
	s_addc_u32 s7, s44, 0
	s_add_u32 s8, s37, 0x600700
	s_addc_u32 s9, s44, 0
	s_add_u32 s10, s37, 0x600800
	s_addc_u32 s11, s44, 0
	s_add_u32 s12, s37, 0x600900
	s_addc_u32 s13, s44, 0
	s_add_u32 s14, s37, 0x600a00
	s_addc_u32 s15, s44, 0
	s_add_u32 s16, s37, 0x600b00
	s_addc_u32 s17, s44, 0
	s_add_u32 s18, s37, 0x600c00
	s_addc_u32 s19, s44, 0
	s_add_u32 s20, s37, 0x600d00
	s_addc_u32 s21, s44, 0
	s_add_u32 s22, s37, 0x600e00
	s_addc_u32 s23, s44, 0
	s_add_u32 s24, s37, 0x600f00
	s_addc_u32 s25, s44, 0
	s_add_u32 s26, s37, 0x601000
	s_addc_u32 s27, s44, 0
	s_add_u32 s28, s37, 0x601100
	s_addc_u32 s29, s44, 0
	s_add_u32 s40, s37, 0x601200
	s_addc_u32 s41, s44, 0
	s_add_u32 s42, s37, 0x601300
	s_addc_u32 s43, s44, 0
	s_mov_b32 s63, 1
	s_mov_b64 s[50:51], 0
	s_branch .LBB0_1295

.LBB0_1342:
	s_waitcnt vmcnt(0) expcnt(0) lgkmcnt(0)
	buffer_inv sc1
	ds_read_b32 v2, v217
	ds_read_b32 v0, v218
	s_and_b32 s62, s0, 15
	s_waitcnt lgkmcnt(1)
	v_cmp_ne_u32_e32 vcc, 0, v2
	s_cbranch_vccnz .LBB0_1356
	s_add_u32 s0, s37, 0x600200
	s_addc_u32 s1, s44, 0
	s_add_u32 s2, s37, 0x600400
	s_addc_u32 s3, s44, 0
	s_add_u32 s4, s37, 0x600500
	s_addc_u32 s5, s44, 0
	s_add_u32 s6, s37, 0x600600
	s_addc_u32 s7, s44, 0
	s_add_u32 s8, s37, 0x600700
	s_addc_u32 s9, s44, 0
	s_add_u32 s10, s37, 0x600800
	s_addc_u32 s11, s44, 0
	s_add_u32 s12, s37, 0x600900
	s_addc_u32 s13, s44, 0
	s_add_u32 s14, s37, 0x600a00
	s_addc_u32 s15, s44, 0
	s_add_u32 s16, s37, 0x600b00
	s_addc_u32 s17, s44, 0
	s_add_u32 s18, s37, 0x600c00
	s_addc_u32 s19, s44, 0
	s_add_u32 s20, s37, 0x600d00
	s_addc_u32 s21, s44, 0
	s_add_u32 s22, s37, 0x600e00
	s_addc_u32 s23, s44, 0
	s_add_u32 s24, s37, 0x600f00
	s_addc_u32 s25, s44, 0
	s_add_u32 s26, s37, 0x601000
	s_addc_u32 s27, s44, 0
	s_add_u32 s28, s37, 0x601100
	s_addc_u32 s29, s44, 0
	s_add_u32 s40, s37, 0x601200
	s_addc_u32 s41, s44, 0
	s_add_u32 s42, s37, 0x601300
	s_addc_u32 s43, s44, 0
	s_mov_b32 s63, 1
	s_mov_b64 s[46:47], 0
	s_branch .LBB0_1346
